# best + DOWN0 meta side-GEMM hook: all 22 operand loads issued up front (one round trip instead of four)
# speedup vs baseline: 1.0006x; 1.0006x over previous
.LBB0_1063:
	global_load_dwordx4 v[48:51], v[12:13], off
	v_add_u32_e32 v1, s0, v45
	v_mad_i64_i32 v[92:93], s[2:3], v1, s7, v[34:35]
	global_load_dwordx4 v[52:55], v[14:15], off
	global_load_dwordx4 v[56:59], v[92:93], off
	global_load_dwordx4 v[60:63], v[92:93], off offset:64
	global_load_dwordx4 v[64:67], v[16:17], off
	global_load_dwordx4 v[68:71], v[18:19], off
	global_load_dwordx4 v[72:75], v[92:93], off offset:128
	global_load_dwordx4 v[76:79], v[92:93], off offset:192
	global_load_dwordx4 v[80:83], v[20:21], off
	global_load_dwordx4 v[84:87], v[22:23], off
	global_load_dwordx4 v[94:97], v[92:93], off offset:256
	global_load_dwordx4 v[98:101], v[92:93], off offset:320
	global_load_dwordx4 v[102:105], v[24:25], off
	global_load_dwordx4 v[106:109], v[26:27], off
	global_load_dwordx4 v[110:113], v[92:93], off offset:384
	global_load_dwordx4 v[114:117], v[28:29], off
	global_load_dwordx4 v[118:121], v[92:93], off offset:448
	global_load_dwordx4 v[122:125], v[92:93], off offset:512
	global_load_dwordx4 v[226:229], v[30:31], off
	global_load_dwordx4 v[230:233], v[92:93], off offset:576
	global_load_dwordx4 v[88:91], v[32:33], off
	global_load_dwordx4 v[234:237], v[92:93], off offset:640
	v_add_u32_e32 v1, s5, v46
	s_waitcnt vmcnt(0)
	v_mfma_f32_16x16x32_bf16 v[48:51], v[48:51], v[56:59], 0
	v_mfma_f32_16x16x32_bf16 v[48:51], v[52:55], v[60:63], v[48:51]
	v_mfma_f32_16x16x32_bf16 v[48:51], v[64:67], v[72:75], v[48:51]
	v_mfma_f32_16x16x32_bf16 v[48:51], v[68:71], v[76:79], v[48:51]
	v_mfma_f32_16x16x32_bf16 v[48:51], v[80:83], v[94:97], v[48:51]
	v_mfma_f32_16x16x32_bf16 v[48:51], v[84:87], v[98:101], v[48:51]
	v_mfma_f32_16x16x32_bf16 v[48:51], v[102:105], v[110:113], v[48:51]
	v_mfma_f32_16x16x32_bf16 v[48:51], v[106:109], v[118:121], v[48:51]
	v_mfma_f32_16x16x32_bf16 v[48:51], v[114:117], v[122:125], v[48:51]
	v_mfma_f32_16x16x32_bf16 v[48:51], v[226:229], v[230:233], v[48:51]
	v_mfma_f32_16x16x32_bf16 v[48:51], v[88:91], v[234:237], v[48:51]
	s_nop 7
	ds_write_b128 v1, v[48:51]
	s_waitcnt lgkmcnt(0)
	s_barrier
	s_and_saveexec_b64 s[2:3], vcc
	s_cbranch_execz .LBB0_1062
	ds_read_b128 v[48:51], v46
	ds_read_b128 v[52:55], v46 offset:1024
	ds_read_b128 v[56:59], v46 offset:2048
	ds_read_b128 v[60:63], v46 offset:3072
	s_ashr_i32 s1, s0, 31
	s_waitcnt lgkmcnt(2)
	v_pk_add_f32 v[50:51], v[50:51], v[54:55]
	v_pk_add_f32 v[52:53], v[48:49], v[52:53]
	s_waitcnt lgkmcnt(1)
	v_pk_add_f32 v[54:55], v[50:51], v[58:59]
	ds_read_b128 v[48:51], v46 offset:4096
	v_pk_add_f32 v[52:53], v[52:53], v[56:57]
	s_waitcnt lgkmcnt(1)
	v_pk_add_f32 v[56:57], v[54:55], v[62:63]
	v_pk_add_f32 v[60:61], v[52:53], v[60:61]
	ds_read_b128 v[52:55], v46 offset:5120
	s_waitcnt lgkmcnt(1)
	v_pk_add_f32 v[62:63], v[56:57], v[50:51]
	ds_read_b128 v[56:59], v46 offset:6144
	v_pk_add_f32 v[60:61], v[60:61], v[48:49]
	ds_read_b128 v[48:51], v46 offset:7168
	s_waitcnt lgkmcnt(2)
	v_pk_add_f32 v[52:53], v[60:61], v[52:53]
	v_pk_add_f32 v[54:55], v[62:63], v[54:55]
	s_waitcnt lgkmcnt(1)
	v_pk_add_f32 v[52:53], v[52:53], v[56:57]
	v_pk_add_f32 v[54:55], v[54:55], v[58:59]
	s_waitcnt lgkmcnt(0)
	v_pk_add_f32 v[48:49], v[52:53], v[48:49]
	v_lshl_add_u64 v[52:53], s[0:1], 2, v[2:3]
	v_pk_add_f32 v[50:51], v[54:55], v[50:51]
	v_lshl_add_u64 v[54:55], v[52:53], 0, v[4:5]
	global_store_dword v[54:55], v48, off
	v_lshl_add_u64 v[54:55], v[52:53], 0, v[6:7]
	global_store_dword v[54:55], v49, off
	v_lshl_add_u64 v[48:49], v[52:53], 0, v[8:9]
	global_store_dword v[48:49], v50, off
	v_lshl_add_u64 v[48:49], v[52:53], 0, v[10:11]
	global_store_dword v[48:49], v51, off
	s_branch .LBB0_1062
